# rotK with the wait before the bias-table reads relaxed to the counter limit (lgkmcnt 7 / 5) so K reads keep flying
# baseline (speedup 1.0000x reference)
; __device__ __forceinline__ unsigned pk2(float lo, float hi) { f32x2_t v = {lo, hi}; bf16x2_t b = __builtin_convertvector(v, bf16x2_t); return __builtin_bit_cast(unsigned, b); }
; __device__ __forceinline__ int crow(int r, int hi) { return (r & 3) + 8 * (r >> 2) + 4 * hi; }
; template <int MODE>
; __device__ __forceinline__ void step64(St& S, const bf16x8 (&qf)[4], int t, int qpos0, bool diag, bool first, float cq, float cfar, const LAS float* tab,
;                                        const LAS unsigned char* buf, unsigned vaddr, int r32, int hi) {
;     ...
;         if (qpos0 - (t * 64 + 31) >= 128) {
;             const float c = cfar - S.m;
; #pragma unroll
;             for (int r = 0; r < 16; ++r) sa[r] = c;
;         } else {
;             const int dd = qpos0 + r32 - t * 64 + 128;
; #pragma unroll
;             for (int r = 0; r < 16; ++r) { int idx = dd - crow(r, hi); idx = idx < 0 ? 0 : (idx > 256 ? 256 : idx); sa[r] = tab[idx] - S.m; }
;     ...
;     for (int r = 0; r < 16; ++r) { sa[r] = __builtin_amdgcn_exp2f(sa[r]); sb[r] = __builtin_amdgcn_exp2f(sb[r]); }
;     asm volatile("s_waitcnt lgkmcnt(0)" ::: "memory");
;     __builtin_amdgcn_sched_barrier(0);
;     u32x4 pa0, pa1, pb0, pb1;
;     pa0.x = pk2(sa[0], sa[1]); pa0.y = pk2(sa[2], sa[3]); pa0.z = pk2(sa[4], sa[5]); pa0.w = pk2(sa[6], sa[7]);
;     pa1.x = pk2(sa[8], sa[9]); pa1.y = pk2(sa[10], sa[11]); pa1.z = pk2(sa[12], sa[13]); pa1.w = pk2(sa[14], sa[15]);
;     pb0.x = pk2(sb[0], sb[1]); pb0.y = pk2(sb[2], sb[3]); pb0.z = pk2(sb[4], sb[5]); pb0.w = pk2(sb[6], sb[7]);
;     pb1.x = pk2(sb[8], sb[9]); pb1.y = pk2(sb[10], sb[11]); pb1.z = pk2(sb[12], sb[13]); pb1.w = pk2(sb[14], sb[15]);
;     ...
;     S.o0 = __builtin_amdgcn_mfma_f32_32x32x16_bf16(ATT_VF(0), ATT_PF(pa0), S.o0, 0, 0, 0);
;     S.o1 = __builtin_amdgcn_mfma_f32_32x32x16_bf16(ATT_VF(2), ATT_PF(pa0), S.o1, 0, 0, 0);
;     S.o0 = __builtin_amdgcn_mfma_f32_32x32x16_bf16(ATT_VF(1), ATT_PF(pa1), S.o0, 0, 0, 0);
;     S.o1 = __builtin_amdgcn_mfma_f32_32x32x16_bf16(ATT_VF(3), ATT_PF(pa1), S.o1, 0, 0, 0);
.Lk0_nodma:
	s_cmp_le_i32 s44, s34
	s_cbranch_scc1 .Lk0_noY
	s_add_i32 s35, s41, 1
	s_cmp_gt_i32 s44, s35
	s_cbranch_scc1 .Lk0_noY
	v_exp_f32_e32 v48, v48
	v_exp_f32_e32 v49, v49
	v_exp_f32_e32 v50, v50
	v_exp_f32_e32 v51, v51
	v_exp_f32_e32 v52, v52
	v_exp_f32_e32 v53, v53
	v_exp_f32_e32 v54, v54
	v_exp_f32_e32 v55, v55
	v_cvt_pk_bf16_f32 v218, v48, v49
	v_cvt_pk_bf16_f32 v219, v50, v51
	v_cvt_pk_bf16_f32 v220, v52, v53
	v_cvt_pk_bf16_f32 v221, v54, v55
	v_exp_f32_e32 v56, v56
	v_exp_f32_e32 v57, v57
	v_mfma_f32_32x32x16_bf16 v[32:47], v[112:115], v[218:221], v[32:47]
	s_cmp_gt_i32 s44, s41
	s_cbranch_scc1 .Lk0a_notab
	s_add_i32 s35, s48, 63
	s_min_i32 s35, s35, 192
	s_lshl_b32 s35, s35, 2
	v_subrev_u32_e32 v235, s35, v238
	s_waitcnt lgkmcnt(5)
	ds_read_b128 v[158:161], v235
	ds_read_b128 v[162:165], v235 offset:32
	ds_read_b128 v[166:169], v235 offset:64
	ds_read_b128 v[170:173], v235 offset:96
	ds_read_b128 v[174:177], v235 offset:128
	ds_read_b128 v[180:183], v235 offset:160
	ds_read_b128 v[116:119], v235 offset:192
	ds_read_b64 v[236:237], v235 offset:224
	ds_read_b32 v178, v235 offset:232
	ds_read_b32 v185, v235 offset:236

; __device__ __forceinline__ unsigned pk2(float lo, float hi) { f32x2_t v = {lo, hi}; bf16x2_t b = __builtin_convertvector(v, bf16x2_t); return __builtin_bit_cast(unsigned, b); }
; template <int MODE>
; __device__ __forceinline__ void step64(St& S, const bf16x8 (&qf)[4], int t, int qpos0, bool diag, bool first, float cq, float cfar, const LAS float* tab,
;                                        const LAS unsigned char* buf, unsigned vaddr, int r32, int hi) {
;     ...
;     for (int r = 0; r < 16; ++r) { sa[r] = __builtin_amdgcn_exp2f(sa[r]); sb[r] = __builtin_amdgcn_exp2f(sb[r]); }
;     asm volatile("s_waitcnt lgkmcnt(0)" ::: "memory");
;     __builtin_amdgcn_sched_barrier(0);
;     u32x4 pa0, pa1, pb0, pb1;
;     pa0.x = pk2(sa[0], sa[1]); pa0.y = pk2(sa[2], sa[3]); pa0.z = pk2(sa[4], sa[5]); pa0.w = pk2(sa[6], sa[7]);
;     pa1.x = pk2(sa[8], sa[9]); pa1.y = pk2(sa[10], sa[11]); pa1.z = pk2(sa[12], sa[13]); pa1.w = pk2(sa[14], sa[15]);
;     pb0.x = pk2(sb[0], sb[1]); pb0.y = pk2(sb[2], sb[3]); pb0.z = pk2(sb[4], sb[5]); pb0.w = pk2(sb[6], sb[7]);
;     pb1.x = pk2(sb[8], sb[9]); pb1.y = pk2(sb[10], sb[11]); pb1.z = pk2(sb[12], sb[13]); pb1.w = pk2(sb[14], sb[15]);
;     ...
;     S.o0 = __builtin_amdgcn_mfma_f32_32x32x16_bf16(ATT_VF(0), ATT_PF(pa0), S.o0, 0, 0, 0);
;     S.o1 = __builtin_amdgcn_mfma_f32_32x32x16_bf16(ATT_VF(2), ATT_PF(pa0), S.o1, 0, 0, 0);
;     S.o0 = __builtin_amdgcn_mfma_f32_32x32x16_bf16(ATT_VF(1), ATT_PF(pa1), S.o0, 0, 0, 0);
;     S.o1 = __builtin_amdgcn_mfma_f32_32x32x16_bf16(ATT_VF(3), ATT_PF(pa1), S.o1, 0, 0, 0);
.Lk0_epi:
	s_add_i32 s35, s41, 1
	s_cmp_gt_i32 s44, s35
	s_cbranch_scc1 .Lk0_done
	v_exp_f32_e32 v48, v48
	v_exp_f32_e32 v49, v49
	v_exp_f32_e32 v50, v50
	v_exp_f32_e32 v51, v51
	v_exp_f32_e32 v52, v52
	v_exp_f32_e32 v53, v53
	v_exp_f32_e32 v54, v54
	v_exp_f32_e32 v55, v55
	v_cvt_pk_bf16_f32 v218, v48, v49
	v_cvt_pk_bf16_f32 v219, v50, v51
	v_cvt_pk_bf16_f32 v220, v52, v53
	v_cvt_pk_bf16_f32 v221, v54, v55
	v_exp_f32_e32 v56, v56
	v_exp_f32_e32 v57, v57
	v_mfma_f32_32x32x16_bf16 v[32:47], v[112:115], v[218:221], v[32:47]
	s_cmp_gt_i32 s44, s41
	s_cbranch_scc1 .Lk0b_notab
	s_add_i32 s35, s48, 63
	s_min_i32 s35, s35, 192
	s_lshl_b32 s35, s35, 2
	v_subrev_u32_e32 v235, s35, v238
	s_waitcnt lgkmcnt(5)
	ds_read_b128 v[158:161], v235
	ds_read_b128 v[162:165], v235 offset:32
	ds_read_b128 v[166:169], v235 offset:64
	ds_read_b128 v[170:173], v235 offset:96
	ds_read_b128 v[174:177], v235 offset:128
	ds_read_b128 v[180:183], v235 offset:160
	ds_read_b128 v[116:119], v235 offset:192
	ds_read_b64 v[236:237], v235 offset:224
	ds_read_b32 v178, v235 offset:232
	ds_read_b32 v185, v235 offset:236

; #define LAS __attribute__((address_space(3)))
; template <int MODE>
; __device__ __forceinline__ void step64(St& S, const bf16x8 (&qf)[4], int t, int qpos0, bool diag, bool first, float cq, float cfar, const LAS float* tab,
;                                        const LAS unsigned char* buf, unsigned vaddr, int r32, int hi) {
;     ...
;     if (MODE == 1) {
;         const float nm = cq - S.m;
; #pragma unroll
;         for (int g = 0; g < 4; ++g) { const f32x4 c0 = *(const LAS f32x4*)(tab + t * 64 + 8 * g + 4 * hi), c1 = *(const LAS f32x4*)(tab + t * 64 + 32 + 8 * g + 4 * hi);
; #pragma unroll
;             for (int e = 0; e < 4; ++e) { sa[4 * g + e] = nm - c0[e]; sb[4 * g + e] = nm - c1[e]; } }
;     ...
;     for (int r = 0; r < 16; ++r) { sa[r] = __builtin_amdgcn_exp2f(sa[r]); sb[r] = __builtin_amdgcn_exp2f(sb[r]); }
;     asm volatile("s_waitcnt lgkmcnt(0)" ::: "memory");
;     __builtin_amdgcn_sched_barrier(0);
;     u32x4 pa0, pa1, pb0, pb1;
;     pa0.x = pk2(sa[0], sa[1]); pa0.y = pk2(sa[2], sa[3]); pa0.z = pk2(sa[4], sa[5]); pa0.w = pk2(sa[6], sa[7]);
;     pa1.x = pk2(sa[8], sa[9]); pa1.y = pk2(sa[10], sa[11]); pa1.z = pk2(sa[12], sa[13]); pa1.w = pk2(sa[14], sa[15]);
;     pb0.x = pk2(sb[0], sb[1]); pb0.y = pk2(sb[2], sb[3]); pb0.z = pk2(sb[4], sb[5]); pb0.w = pk2(sb[6], sb[7]);
;     pb1.x = pk2(sb[8], sb[9]); pb1.y = pk2(sb[10], sb[11]); pb1.z = pk2(sb[12], sb[13]); pb1.w = pk2(sb[14], sb[15]);
;     ...
;     S.o0 = __builtin_amdgcn_mfma_f32_32x32x16_bf16(ATT_VF(0), ATT_PF(pa0), S.o0, 0, 0, 0);
;     S.o1 = __builtin_amdgcn_mfma_f32_32x32x16_bf16(ATT_VF(2), ATT_PF(pa0), S.o1, 0, 0, 0);
;     S.o0 = __builtin_amdgcn_mfma_f32_32x32x16_bf16(ATT_VF(1), ATT_PF(pa1), S.o0, 0, 0, 0);
;     S.o1 = __builtin_amdgcn_mfma_f32_32x32x16_bf16(ATT_VF(3), ATT_PF(pa1), S.o1, 0, 0, 0);
;     S.o0 = __builtin_amdgcn_mfma_f32_32x32x16_bf16(ATT_VF(4), ATT_PF(pb0), S.o0, 0, 0, 0);
;     S.o1 = __builtin_amdgcn_mfma_f32_32x32x16_bf16(ATT_VF(6), ATT_PF(pb0), S.o1, 0, 0, 0);
;     S.o0 = __builtin_amdgcn_mfma_f32_32x32x16_bf16(ATT_VF(5), ATT_PF(pb1), S.o0, 0, 0, 0);
;     S.o1 = __builtin_amdgcn_mfma_f32_32x32x16_bf16(ATT_VF(7), ATT_PF(pb1), S.o1, 0, 0, 0);
;     ...
;     float l0 = 0.f, l1 = 0.f, l2 = 0.f, l3 = 0.f;
; #pragma unroll
;     for (int r = 0; r < 16; r += 2) { l0 += sa[r]; l1 += sa[r + 1]; l2 += sb[r]; l3 += sb[r + 1]; }
;     S.l += (l0 + l1) + (l2 + l3);
.Lk1_nodma:
	s_cmp_lt_i32 s22, s28
	s_cbranch_scc0 .Lk1_noY
	v_exp_f32_e32 v48, v48
	v_exp_f32_e32 v49, v49
	v_exp_f32_e32 v50, v50
	v_exp_f32_e32 v51, v51
	v_exp_f32_e32 v52, v52
	v_exp_f32_e32 v53, v53
	v_exp_f32_e32 v54, v54
	v_exp_f32_e32 v55, v55
	v_cvt_pk_bf16_f32 v152, v48, v49
	v_cvt_pk_bf16_f32 v153, v50, v51
	v_cvt_pk_bf16_f32 v154, v52, v53
	v_cvt_pk_bf16_f32 v155, v54, v55
	v_exp_f32_e32 v56, v56
	v_exp_f32_e32 v57, v57
	v_mfma_f32_32x32x16_bf16 v[32:47], v[112:115], v[152:155], v[32:47]
	s_waitcnt lgkmcnt(7)
	ds_read_b128 v[164:167], v148
	ds_read_b128 v[168:171], v148 offset:32
	ds_read_b128 v[172:175], v148 offset:64
	ds_read_b128 v[180:183], v148 offset:96
	ds_read_b128 v[218:221], v148 offset:128
	ds_read_b128 v[222:225], v148 offset:160
	ds_read_b128 v[226:229], v148 offset:192
	ds_read_b128 v[230:233], v148 offset:224
	v_exp_f32_e32 v58, v58
	v_exp_f32_e32 v59, v59
	v_exp_f32_e32 v60, v60
	v_exp_f32_e32 v61, v61
	v_exp_f32_e32 v62, v62
	v_exp_f32_e32 v63, v63
	v_mfma_f32_32x32x16_bf16 v[16:31], v[108:111], v[152:155], v[16:31]
	v_cvt_pk_bf16_f32 v156, v56, v57
	v_cvt_pk_bf16_f32 v157, v58, v59
	v_cvt_pk_bf16_f32 v158, v60, v61
	v_cvt_pk_bf16_f32 v159, v62, v63
	v_add_f32_e32 v0, v48, v50
	v_add_f32_e32 v0, v0, v52
	v_add_f32_e32 v14, v49, v51
	v_add_f32_e32 v14, v14, v53
	v_mfma_f32_32x32x16_bf16 v[32:47], v[104:107], v[156:159], v[32:47]
	v_exp_f32_e32 v64, v64
	v_exp_f32_e32 v65, v65
	v_exp_f32_e32 v66, v66
	v_exp_f32_e32 v67, v67
	v_exp_f32_e32 v68, v68
	v_exp_f32_e32 v69, v69
	v_exp_f32_e32 v70, v70
	v_exp_f32_e32 v71, v71
	v_mfma_f32_32x32x16_bf16 v[16:31], v[100:103], v[156:159], v[16:31]
	v_cvt_pk_bf16_f32 v160, v64, v65
	v_cvt_pk_bf16_f32 v161, v66, v67
	v_cvt_pk_bf16_f32 v162, v68, v69
	v_cvt_pk_bf16_f32 v163, v70, v71
	v_add_f32_e32 v0, v0, v54
	v_add_f32_e32 v0, v0, v56
	v_add_f32_e32 v14, v14, v55
	v_add_f32_e32 v14, v14, v57
	v_mfma_f32_32x32x16_bf16 v[32:47], v[96:99], v[160:163], v[32:47]
	v_exp_f32_e32 v72, v72
	v_exp_f32_e32 v73, v73
	v_exp_f32_e32 v74, v74
	v_exp_f32_e32 v75, v75
	v_exp_f32_e32 v76, v76
	v_exp_f32_e32 v77, v77
	v_exp_f32_e32 v78, v78
	v_exp_f32_e32 v79, v79
	v_mfma_f32_32x32x16_bf16 v[16:31], v[10:13], v[160:163], v[16:31]
	v_cvt_pk_bf16_f32 v234, v72, v73
	v_cvt_pk_bf16_f32 v235, v74, v75
	v_cvt_pk_bf16_f32 v236, v76, v77
	v_cvt_pk_bf16_f32 v237, v78, v79
	v_add_f32_e32 v0, v0, v58
	v_add_f32_e32 v0, v0, v60
	v_add_f32_e32 v0, v0, v62
	v_add_f32_e32 v14, v14, v59
	v_add_f32_e32 v14, v14, v61
	v_add_f32_e32 v14, v14, v63
	v_mfma_f32_32x32x16_bf16 v[32:47], v[6:9], v[234:237], v[32:47]
	v_add_f32_e32 v15, v64, v66
	v_add_f32_e32 v15, v15, v68
	v_add_f32_e32 v15, v15, v70
	v_add_f32_e32 v15, v15, v72
	v_add_f32_e32 v151, v65, v67
	v_add_f32_e32 v151, v151, v69
	v_add_f32_e32 v151, v151, v71
	v_add_f32_e32 v151, v151, v73
	v_mfma_f32_32x32x16_bf16 v[16:31], v[2:5], v[234:237], v[16:31]
	v_add_f32_e32 v15, v15, v74
	v_add_f32_e32 v15, v15, v76
	v_add_f32_e32 v15, v15, v78
	v_add_f32_e32 v151, v151, v75
	v_add_f32_e32 v151, v151, v77
	v_add_f32_e32 v151, v151, v79
	v_add_f32_e32 v0, v0, v14
	v_add_f32_e32 v15, v15, v151
	v_add_f32_e32 v0, v0, v15
	v_add_f32_e32 v149, v149, v0
	v_sub_f32_e32 v151, v142, v150
	s_waitcnt lgkmcnt(0)
	v_sub_f32_e32 v48, v151, v164
	v_sub_f32_e32 v49, v151, v165
	v_sub_f32_e32 v50, v151, v166
	v_sub_f32_e32 v51, v151, v167
	v_sub_f32_e32 v52, v151, v168
	v_sub_f32_e32 v53, v151, v169
	v_sub_f32_e32 v54, v151, v170
	v_sub_f32_e32 v55, v151, v171
	v_sub_f32_e32 v56, v151, v172
	v_sub_f32_e32 v57, v151, v173
	v_sub_f32_e32 v58, v151, v174
	v_sub_f32_e32 v59, v151, v175
	v_sub_f32_e32 v60, v151, v180
	v_sub_f32_e32 v61, v151, v181
	v_sub_f32_e32 v62, v151, v182
	v_sub_f32_e32 v63, v151, v183
	v_sub_f32_e32 v64, v151, v218
	v_sub_f32_e32 v65, v151, v219
	v_sub_f32_e32 v66, v151, v220
	v_sub_f32_e32 v67, v151, v221
	v_sub_f32_e32 v68, v151, v222
	v_sub_f32_e32 v69, v151, v223
	v_sub_f32_e32 v70, v151, v224
	v_sub_f32_e32 v71, v151, v225
	v_sub_f32_e32 v72, v151, v226
	v_sub_f32_e32 v73, v151, v227
	v_sub_f32_e32 v74, v151, v228
	v_sub_f32_e32 v75, v151, v229
	v_sub_f32_e32 v76, v151, v230
	v_sub_f32_e32 v77, v151, v231
	v_sub_f32_e32 v78, v151, v232
	v_sub_f32_e32 v79, v151, v233
